# all four GEMM k-loops: LDS-DMA in scalar-base form with immediate offsets, A-fragment LDS reads via invariant base (no VALU in load segments)
# speedup vs baseline: 1.0087x; 1.0018x over previous
.LBB0_25:
	ds_read_b128 v[132:135], v181
	ds_read_b128 v[136:139], v182
	ds_read_b128 v[140:143], v183
	ds_read_b128 v[144:147], v184
	ds_read_b128 v[148:151], v185
	ds_read_b128 v[152:155], v186
	ds_read_b128 v[156:159], v187
	ds_read_b128 v[160:163], v188
	s_add_i32 s73, s28, 2
	s_add_u32 s26, s22, 0x80
	s_addc_u32 s27, s23, 0
	s_cmp_eq_u32 s54, s28
	s_cselect_b32 s28, s16, s26
	s_cselect_b32 s29, s17, s27
	s_cselect_b32 s27, s21, s72
	s_cselect_b32 s26, s20, s55
	s_mov_b32 m0, s46
	ds_read_b128 v[198:201], v179
	ds_read_b128 v[202:205], v179 offset:1024
	ds_read_b128 v[206:209], v179 offset:2048
	ds_read_b128 v[210:213], v179 offset:3072
	ds_read_b128 v[214:217], v179 offset:4096
	ds_read_b128 v[218:221], v179 offset:5120
	ds_read_b128 v[222:225], v179 offset:6144
	ds_read_b128 v[242:245], v179 offset:7168
	global_load_lds_dwordx4 v172, s[22:23]
	s_mov_b32 m0, s47
	s_nop 0
	global_load_lds_dwordx4 v174, s[22:23]
	s_waitcnt vmcnt(8)
	s_waitcnt lgkmcnt(0)
	s_barrier
	s_setprio 1
	s_waitcnt lgkmcnt(0)
	v_mfma_f32_16x16x32_bf16 v[128:131], v[132:135], v[198:201], v[128:131]
	v_mfma_f32_16x16x32_bf16 v[124:127], v[140:143], v[198:201], v[124:127]
	v_mfma_f32_16x16x32_bf16 v[120:123], v[132:135], v[206:209], v[120:123]
	v_mfma_f32_16x16x32_bf16 v[116:119], v[140:143], v[206:209], v[116:119]
	v_mfma_f32_16x16x32_bf16 v[112:115], v[132:135], v[214:217], v[112:115]
	v_mfma_f32_16x16x32_bf16 v[108:111], v[140:143], v[214:217], v[108:111]
	v_mfma_f32_16x16x32_bf16 v[104:107], v[132:135], v[222:225], v[104:107]
	v_mfma_f32_16x16x32_bf16 v[100:103], v[140:143], v[222:225], v[100:103]
	v_mfma_f32_16x16x32_bf16 v[128:131], v[136:139], v[202:205], v[128:131]
	v_mfma_f32_16x16x32_bf16 v[124:127], v[144:147], v[202:205], v[124:127]
	v_mfma_f32_16x16x32_bf16 v[120:123], v[136:139], v[210:213], v[120:123]
	v_mfma_f32_16x16x32_bf16 v[116:119], v[144:147], v[210:213], v[116:119]
	v_mfma_f32_16x16x32_bf16 v[112:115], v[136:139], v[218:221], v[112:115]
	v_mfma_f32_16x16x32_bf16 v[108:111], v[144:147], v[218:221], v[108:111]
	v_mfma_f32_16x16x32_bf16 v[104:107], v[136:139], v[242:245], v[104:107]
	v_mfma_f32_16x16x32_bf16 v[100:103], v[144:147], v[242:245], v[100:103]
	s_setprio 0
	s_setprio 1
	v_mfma_f32_16x16x32_bf16 v[96:99], v[148:151], v[198:201], v[96:99]
	v_mfma_f32_16x16x32_bf16 v[92:95], v[156:159], v[198:201], v[92:95]
	v_mfma_f32_16x16x32_bf16 v[88:91], v[148:151], v[206:209], v[88:91]
	v_mfma_f32_16x16x32_bf16 v[84:87], v[156:159], v[206:209], v[84:87]
	v_mfma_f32_16x16x32_bf16 v[80:83], v[148:151], v[214:217], v[80:83]
	v_mfma_f32_16x16x32_bf16 v[76:79], v[156:159], v[214:217], v[76:79]
	v_mfma_f32_16x16x32_bf16 v[72:75], v[148:151], v[222:225], v[72:75]
	v_mfma_f32_16x16x32_bf16 v[66:69], v[156:159], v[222:225], v[68:71]
	v_mfma_f32_16x16x32_bf16 v[96:99], v[152:155], v[202:205], v[96:99]
	v_mfma_f32_16x16x32_bf16 v[92:95], v[160:163], v[202:205], v[92:95]
	v_mfma_f32_16x16x32_bf16 v[88:91], v[152:155], v[210:213], v[88:91]
	v_mfma_f32_16x16x32_bf16 v[84:87], v[160:163], v[210:213], v[84:87]
	v_mfma_f32_16x16x32_bf16 v[80:83], v[152:155], v[218:221], v[80:83]
	v_mfma_f32_16x16x32_bf16 v[76:79], v[160:163], v[218:221], v[76:79]
	v_mfma_f32_16x16x32_bf16 v[72:75], v[152:155], v[242:245], v[72:75]
	v_mfma_f32_16x16x32_bf16 v[66:69], v[160:163], v[242:245], v[66:69]
	s_setprio 0
	s_barrier
	s_mov_b32 m0, s31
	s_add_u32 s74, s26, 0x80000
	s_addc_u32 s75, s27, 0
	ds_read_b128 v[198:201], v179 offset:16384
	ds_read_b128 v[202:205], v179 offset:17408
	ds_read_b128 v[206:209], v179 offset:18432
	ds_read_b128 v[210:213], v179 offset:19456
	ds_read_b128 v[214:217], v179 offset:20480
	ds_read_b128 v[218:221], v179 offset:21504
	ds_read_b128 v[222:225], v179 offset:22528
	ds_read_b128 v[242:245], v179 offset:23552
	global_load_lds_dwordx4 v168, s[26:27]
	s_mov_b32 m0, s34
	s_nop 0
	global_load_lds_dwordx4 v164, s[26:27]
	s_mov_b32 m0, s35
	s_nop 0
	global_load_lds_dwordx4 v168, s[74:75]
	s_mov_b32 m0, s36
	s_nop 0
	global_load_lds_dwordx4 v164, s[74:75]
	s_mov_b32 m0, s30
	s_nop 0
	global_load_lds_dwordx4 v170, s[28:29]
	s_mov_b32 m0, s37
	s_nop 0
	global_load_lds_dwordx4 v166, s[28:29]
	s_waitcnt vmcnt(8)
	s_waitcnt lgkmcnt(0)
	s_barrier
	s_setprio 1
	s_waitcnt lgkmcnt(0)
	v_mfma_f32_16x16x32_bf16 v[60:63], v[132:135], v[198:201], v[60:63]
	v_mfma_f32_16x16x32_bf16 v[56:59], v[140:143], v[198:201], v[56:59]
	v_mfma_f32_16x16x32_bf16 v[52:55], v[132:135], v[206:209], v[52:55]
	v_mfma_f32_16x16x32_bf16 v[48:51], v[140:143], v[206:209], v[48:51]
	v_mfma_f32_16x16x32_bf16 v[44:47], v[132:135], v[214:217], v[44:47]
	v_mfma_f32_16x16x32_bf16 v[40:43], v[140:143], v[214:217], v[40:43]
	v_mfma_f32_16x16x32_bf16 v[36:39], v[132:135], v[222:225], v[36:39]
	v_mfma_f32_16x16x32_bf16 v[32:35], v[140:143], v[222:225], v[32:35]
	v_mfma_f32_16x16x32_bf16 v[60:63], v[136:139], v[202:205], v[60:63]
	v_mfma_f32_16x16x32_bf16 v[56:59], v[144:147], v[202:205], v[56:59]
	v_mfma_f32_16x16x32_bf16 v[52:55], v[136:139], v[210:213], v[52:55]
	v_mfma_f32_16x16x32_bf16 v[48:51], v[144:147], v[210:213], v[48:51]
	v_mfma_f32_16x16x32_bf16 v[44:47], v[136:139], v[218:221], v[44:47]
	v_mfma_f32_16x16x32_bf16 v[40:43], v[144:147], v[218:221], v[40:43]
	v_mfma_f32_16x16x32_bf16 v[36:39], v[136:139], v[242:245], v[36:39]
	v_mfma_f32_16x16x32_bf16 v[32:35], v[144:147], v[242:245], v[32:35]
	s_setprio 0
	s_setprio 1
	v_mfma_f32_16x16x32_bf16 v[28:31], v[148:151], v[198:201], v[28:31]
	v_mfma_f32_16x16x32_bf16 v[24:27], v[156:159], v[198:201], v[24:27]
	v_mfma_f32_16x16x32_bf16 v[20:23], v[148:151], v[206:209], v[20:23]
	v_mfma_f32_16x16x32_bf16 v[16:19], v[156:159], v[206:209], v[16:19]
	v_mfma_f32_16x16x32_bf16 v[12:15], v[148:151], v[214:217], v[12:15]
	v_mfma_f32_16x16x32_bf16 v[8:11], v[156:159], v[214:217], v[8:11]
	v_mfma_f32_16x16x32_bf16 v[4:7], v[148:151], v[222:225], v[4:7]
	v_mfma_f32_16x16x32_bf16 v[0:3], v[156:159], v[222:225], v[0:3]
	v_mfma_f32_16x16x32_bf16 v[28:31], v[152:155], v[202:205], v[28:31]
	v_mfma_f32_16x16x32_bf16 v[24:27], v[160:163], v[202:205], v[24:27]
	v_mfma_f32_16x16x32_bf16 v[20:23], v[152:155], v[210:213], v[20:23]
	v_mfma_f32_16x16x32_bf16 v[16:19], v[160:163], v[210:213], v[16:19]
	v_mfma_f32_16x16x32_bf16 v[12:15], v[152:155], v[218:221], v[12:15]
	v_mfma_f32_16x16x32_bf16 v[8:11], v[160:163], v[218:221], v[8:11]
	v_mfma_f32_16x16x32_bf16 v[4:7], v[152:155], v[242:245], v[4:7]
	v_mfma_f32_16x16x32_bf16 v[0:3], v[160:163], v[242:245], v[0:3]
	s_setprio 0
	s_barrier
	ds_read_b128 v[132:135], v189
	ds_read_b128 v[136:139], v190
	ds_read_b128 v[140:143], v191
	ds_read_b128 v[144:147], v192
	ds_read_b128 v[148:151], v193
	ds_read_b128 v[152:155], v195
	ds_read_b128 v[156:159], v196
	ds_read_b128 v[160:163], v197
	s_add_u32 s56, s28, s92
	s_addc_u32 s57, s29, 0
	s_mov_b32 m0, s38
	ds_read_b128 v[198:201], v179 offset:32768
	ds_read_b128 v[202:205], v179 offset:33792
	ds_read_b128 v[206:209], v179 offset:34816
	ds_read_b128 v[210:213], v179 offset:35840
	ds_read_b128 v[214:217], v179 offset:36864
	ds_read_b128 v[218:221], v179 offset:37888
	ds_read_b128 v[222:225], v179 offset:38912
	ds_read_b128 v[242:245], v179 offset:39936
	global_load_lds_dwordx4 v170, s[56:57]
	s_mov_b32 m0, s39
	s_nop 0
	global_load_lds_dwordx4 v166, s[56:57]
	s_waitcnt vmcnt(8)
	s_waitcnt lgkmcnt(0)
	s_barrier
	s_setprio 1
	s_waitcnt lgkmcnt(0)
	v_mfma_f32_16x16x32_bf16 v[128:131], v[132:135], v[198:201], v[128:131]
	v_mfma_f32_16x16x32_bf16 v[124:127], v[140:143], v[198:201], v[124:127]
	v_mfma_f32_16x16x32_bf16 v[120:123], v[132:135], v[206:209], v[120:123]
	v_mfma_f32_16x16x32_bf16 v[116:119], v[140:143], v[206:209], v[116:119]
	v_mfma_f32_16x16x32_bf16 v[112:115], v[132:135], v[214:217], v[112:115]
	v_mfma_f32_16x16x32_bf16 v[108:111], v[140:143], v[214:217], v[108:111]
	v_mfma_f32_16x16x32_bf16 v[104:107], v[132:135], v[222:225], v[104:107]
	v_mfma_f32_16x16x32_bf16 v[100:103], v[140:143], v[222:225], v[100:103]
	v_mfma_f32_16x16x32_bf16 v[128:131], v[136:139], v[202:205], v[128:131]
	v_mfma_f32_16x16x32_bf16 v[124:127], v[144:147], v[202:205], v[124:127]
	v_mfma_f32_16x16x32_bf16 v[120:123], v[136:139], v[210:213], v[120:123]
	v_mfma_f32_16x16x32_bf16 v[116:119], v[144:147], v[210:213], v[116:119]
	v_mfma_f32_16x16x32_bf16 v[112:115], v[136:139], v[218:221], v[112:115]
	v_mfma_f32_16x16x32_bf16 v[108:111], v[144:147], v[218:221], v[108:111]
	v_mfma_f32_16x16x32_bf16 v[104:107], v[136:139], v[242:245], v[104:107]
	v_mfma_f32_16x16x32_bf16 v[100:103], v[144:147], v[242:245], v[100:103]
	s_setprio 0
	s_setprio 1
	v_mfma_f32_16x16x32_bf16 v[96:99], v[148:151], v[198:201], v[96:99]
	v_mfma_f32_16x16x32_bf16 v[92:95], v[156:159], v[198:201], v[92:95]
	v_mfma_f32_16x16x32_bf16 v[88:91], v[148:151], v[206:209], v[88:91]
	v_mfma_f32_16x16x32_bf16 v[84:87], v[156:159], v[206:209], v[84:87]
	v_mfma_f32_16x16x32_bf16 v[80:83], v[148:151], v[214:217], v[80:83]
	v_mfma_f32_16x16x32_bf16 v[76:79], v[156:159], v[214:217], v[76:79]
	v_mfma_f32_16x16x32_bf16 v[70:73], v[148:151], v[222:225], v[72:75]
	v_mfma_f32_16x16x32_bf16 v[66:69], v[156:159], v[222:225], v[66:69]
	v_mfma_f32_16x16x32_bf16 v[96:99], v[152:155], v[202:205], v[96:99]
	v_mfma_f32_16x16x32_bf16 v[92:95], v[160:163], v[202:205], v[92:95]
	v_mfma_f32_16x16x32_bf16 v[88:91], v[152:155], v[210:213], v[88:91]
	v_mfma_f32_16x16x32_bf16 v[84:87], v[160:163], v[210:213], v[84:87]
	v_mfma_f32_16x16x32_bf16 v[80:83], v[152:155], v[218:221], v[80:83]
	v_mfma_f32_16x16x32_bf16 v[76:79], v[160:163], v[218:221], v[76:79]
	v_mfma_f32_16x16x32_bf16 v[72:75], v[152:155], v[242:245], v[70:73]
	v_mfma_f32_16x16x32_bf16 v[68:71], v[160:163], v[242:245], v[66:69]
	s_setprio 0
	s_barrier
	s_add_i32 m0, s40, 0xffffff80
	s_add_u32 s58, s26, 0x80080
	s_addc_u32 s59, s27, 0
	ds_read_b128 v[198:201], v179 offset:49152
	ds_read_b128 v[202:205], v179 offset:50176
	ds_read_b128 v[206:209], v179 offset:51200
	ds_read_b128 v[210:213], v179 offset:52224
	ds_read_b128 v[214:217], v179 offset:53248
	ds_read_b128 v[218:221], v179 offset:54272
	ds_read_b128 v[222:225], v179 offset:55296
	ds_read_b128 v[242:245], v179 offset:56320
	global_load_lds_dwordx4 v168, s[26:27] offset:128
	s_add_i32 m0, s41, 0xffffff80
	s_nop 0
	global_load_lds_dwordx4 v164, s[26:27] offset:128
	s_mov_b32 m0, s44
	s_nop 0
	global_load_lds_dwordx4 v168, s[58:59]
	s_mov_b32 m0, s45
	s_nop 0
	global_load_lds_dwordx4 v164, s[58:59]
	s_add_i32 m0, s42, 0xffffff80
	s_nop 0
	global_load_lds_dwordx4 v170, s[28:29] offset:128
	s_add_i32 m0, s43, 0xffffff80
	s_nop 0
	global_load_lds_dwordx4 v166, s[28:29] offset:128
	s_waitcnt vmcnt(8)
	s_waitcnt lgkmcnt(0)
	s_barrier
	s_setprio 1
	s_waitcnt lgkmcnt(0)
	v_mfma_f32_16x16x32_bf16 v[60:63], v[132:135], v[198:201], v[60:63]
	v_mfma_f32_16x16x32_bf16 v[56:59], v[140:143], v[198:201], v[56:59]
	v_mfma_f32_16x16x32_bf16 v[52:55], v[132:135], v[206:209], v[52:55]
	v_mfma_f32_16x16x32_bf16 v[48:51], v[140:143], v[206:209], v[48:51]
	v_mfma_f32_16x16x32_bf16 v[44:47], v[132:135], v[214:217], v[44:47]
	v_mfma_f32_16x16x32_bf16 v[40:43], v[140:143], v[214:217], v[40:43]
	v_mfma_f32_16x16x32_bf16 v[36:39], v[132:135], v[222:225], v[36:39]
	v_mfma_f32_16x16x32_bf16 v[32:35], v[140:143], v[222:225], v[32:35]
	v_mfma_f32_16x16x32_bf16 v[60:63], v[136:139], v[202:205], v[60:63]
	v_mfma_f32_16x16x32_bf16 v[56:59], v[144:147], v[202:205], v[56:59]
	v_mfma_f32_16x16x32_bf16 v[52:55], v[136:139], v[210:213], v[52:55]
	v_mfma_f32_16x16x32_bf16 v[48:51], v[144:147], v[210:213], v[48:51]
	v_mfma_f32_16x16x32_bf16 v[44:47], v[136:139], v[218:221], v[44:47]
	v_mfma_f32_16x16x32_bf16 v[40:43], v[144:147], v[218:221], v[40:43]
	v_mfma_f32_16x16x32_bf16 v[36:39], v[136:139], v[242:245], v[36:39]
	v_mfma_f32_16x16x32_bf16 v[32:35], v[144:147], v[242:245], v[32:35]
	s_setprio 0
	s_setprio 1
	v_mfma_f32_16x16x32_bf16 v[28:31], v[148:151], v[198:201], v[28:31]
	v_mfma_f32_16x16x32_bf16 v[24:27], v[156:159], v[198:201], v[24:27]
	v_mfma_f32_16x16x32_bf16 v[20:23], v[148:151], v[206:209], v[20:23]
	v_mfma_f32_16x16x32_bf16 v[16:19], v[156:159], v[206:209], v[16:19]
	v_mfma_f32_16x16x32_bf16 v[12:15], v[148:151], v[214:217], v[12:15]
	v_mfma_f32_16x16x32_bf16 v[8:11], v[156:159], v[214:217], v[8:11]
	v_mfma_f32_16x16x32_bf16 v[4:7], v[148:151], v[222:225], v[4:7]
	v_mfma_f32_16x16x32_bf16 v[0:3], v[156:159], v[222:225], v[0:3]
	v_mfma_f32_16x16x32_bf16 v[28:31], v[152:155], v[202:205], v[28:31]
	v_mfma_f32_16x16x32_bf16 v[24:27], v[160:163], v[202:205], v[24:27]
	v_mfma_f32_16x16x32_bf16 v[20:23], v[152:155], v[210:213], v[20:23]
	v_mfma_f32_16x16x32_bf16 v[16:19], v[160:163], v[210:213], v[16:19]
	v_mfma_f32_16x16x32_bf16 v[12:15], v[152:155], v[218:221], v[12:15]
	v_mfma_f32_16x16x32_bf16 v[8:11], v[160:163], v[218:221], v[8:11]
	v_mfma_f32_16x16x32_bf16 v[4:7], v[152:155], v[242:245], v[4:7]
	v_mfma_f32_16x16x32_bf16 v[0:3], v[160:163], v[242:245], v[0:3]
	s_setprio 0
	s_barrier
	s_add_u32 s22, s22, 0x100
	s_addc_u32 s23, s23, 0
	s_add_u32 s55, s55, 0x100
	s_addc_u32 s72, s72, 0
	s_cmp_ge_u32 s73, s13
	s_mov_b32 s28, s73
	s_cbranch_scc0 .LBB0_25
	s_and_b64 vcc, exec, s[10:11]
	s_cbranch_vccz .LBB0_28
	s_barrier

.LBB0_164:
	v_readlane_b32 s8, v254, 56
	s_lshl_b32 s8, s8, 1
	v_readlane_b32 s9, v254, 57
	s_or_b32 s8, s8, 1
	s_ashr_i32 s9, s8, 31
	s_lshl_b64 s[8:9], s[8:9], 16
	v_readlane_b32 s14, v254, 54
	v_lshrrev_b32_e32 v15, 1, v194
	v_readlane_b32 s15, v254, 55
	s_add_u32 s8, s14, s8
	v_and_b32_e32 v15, 24, v15
	v_lshl_add_u64 v[6:7], s[26:27], 0, v[64:65]
	v_mov_b32_e32 v131, v65
	s_addc_u32 s9, s15, s9
	v_and_b32_e32 v14, 15, v194
	v_lshlrev_b32_e32 v16, 1, v15
	s_lshl_b32 s11, s11, 5
	s_add_i32 s38, s2, 0x18000
	v_lshl_add_u64 v[8:9], s[26:27], 0, v[130:131]
	v_mov_b32_e32 v135, v65
	v_lshl_or_b32 v144, s12, 6, v14
	v_lshl_or_b32 v14, v14, 6, v16
	v_lshlrev_b32_e32 v16, 2, v194
	s_and_b32 s14, s11, 0x60
	v_lshl_add_u64 v[6:7], v[6:7], 0, s[98:99]
	s_mov_b32 m0, s38
	s_add_i32 s39, s2, 0x1a000
	v_lshl_add_u64 v[10:11], s[24:25], 0, v[134:135]
	v_mov_b32_e32 v133, v65
	s_lshl_b32 s12, s12, 13
	v_and_b32_e32 v16, 32, v16
	s_lshl_b32 s11, s14, 7
	s_waitcnt vmcnt(2)
	s_barrier
	global_load_lds_dwordx4 v[6:7], off
	v_lshl_add_u64 v[6:7], v[8:9], 0, s[98:99]
	s_mov_b32 m0, s39
	s_add_i32 s40, s2, 0x8000
	s_add_i32 s41, s2, 0xa000
	v_lshl_add_u64 v[12:13], s[24:25], 0, v[132:133]
	v_bitop3_b32 v145, v14, s12, v16 bitop3:0xde
	global_load_lds_dwordx4 v[6:7], off
	v_lshl_add_u64 v[6:7], v[10:11], 0, s[98:99]
	s_mov_b32 m0, s40
	s_add_u32 s12, s26, 0x80080
	global_load_lds_dwordx4 v[6:7], off
	v_lshl_add_u64 v[6:7], v[12:13], 0, s[98:99]
	s_mov_b32 m0, s41
	s_addc_u32 s13, s27, 0
	s_add_i32 s42, s2, 0x1c000
	global_load_lds_dwordx4 v[6:7], off
	v_lshl_add_u64 v[6:7], s[12:13], 0, v[64:65]
	s_mov_b32 m0, s42
	s_add_i32 s43, s2, 0x1e000
	global_load_lds_dwordx4 v[6:7], off
	v_lshl_add_u64 v[6:7], s[12:13], 0, v[130:131]
	s_mov_b32 m0, s43
	s_cmpk_lt_u32 s10, 0x100
	global_load_lds_dwordx4 v[6:7], off
	v_lshlrev_b32_e32 v6, 15, v4
	v_and_b32_e32 v6, 0xffff0000, v6
	v_lshl_add_u32 v3, v3, 12, v6
	v_and_b32_e32 v4, 1, v4
	v_lshl_or_b32 v3, v4, 6, v3
	v_lshl_add_u32 v136, v5, 1, v3
	v_lshlrev_b32_e32 v3, 15, v0
	v_and_b32_e32 v3, 0xffff0000, v3
	s_waitcnt vmcnt(6)
	v_lshl_add_u32 v1, v1, 12, v3
	v_and_b32_e32 v0, 1, v0
	v_lshl_or_b32 v0, v0, 6, v1
	v_readlane_b32 s12, v254, 25
	v_bitop3_b32 v146, s11, v14, v16 bitop3:0xf6
	s_cselect_b64 s[10:11], -1, 0
	v_or_b32_e32 v147, s14, v15
	v_mov_b32_e32 v137, v65
	v_lshl_add_u32 v138, v2, 1, v0
	v_mov_b32_e32 v139, v65
	s_mov_b32 s44, 0
	v_readlane_b32 s45, v254, 24
	s_mov_b32 s46, s12
	s_barrier
	v_readlane_b32 s13, v254, 26
	v_add_u32_e32 v220, 0x10000, v146
	s_branch .LBB0_167

.LBB0_170:
	ds_read_b128 v[140:143], v220
	ds_read_b128 v[148:151], v220 offset:1024
	ds_read_b128 v[152:155], v220 offset:2048
	ds_read_b128 v[156:159], v220 offset:3072
	ds_read_b128 v[160:163], v220 offset:16384
	ds_read_b128 v[164:167], v220 offset:17408
	ds_read_b128 v[168:171], v220 offset:18432
	ds_read_b128 v[172:175], v220 offset:19456
	s_add_u32 s26, s24, 0xfff80080
	s_addc_u32 s27, s25, -1
	s_cmp_eq_u32 s51, 28
	s_cselect_b32 s29, s13, s27
	s_cselect_b32 s28, s47, s26
	s_cselect_b32 s27, s15, s50
	s_cselect_b32 s26, s48, s49
	s_add_i32 m0, s2, 0xc000
	ds_read_b128 v[176:179], v145
	ds_read_b128 v[180:183], v145 offset:1024
	ds_read_b128 v[184:187], v145 offset:2048
	ds_read_b128 v[188:191], v145 offset:3072
	ds_read_b128 v[196:199], v145 offset:4096
	ds_read_b128 v[200:203], v145 offset:5120
	ds_read_b128 v[204:207], v145 offset:6144
	ds_read_b128 v[208:211], v145 offset:7168
	global_load_lds_dwordx4 v136, s[24:25]
	s_add_i32 m0, s2, 0xe000
	s_nop 0
	global_load_lds_dwordx4 v138, s[24:25]
	s_waitcnt vmcnt(8)
	s_waitcnt lgkmcnt(0)
	s_barrier
	s_setprio 1
	s_waitcnt lgkmcnt(0)
	v_mfma_f32_16x16x32_bf16 v[126:129], v[140:143], v[176:179], v[126:129]
	v_mfma_f32_16x16x32_bf16 v[122:125], v[152:155], v[176:179], v[122:125]
	v_mfma_f32_16x16x32_bf16 v[110:113], v[140:143], v[184:187], v[110:113]
	v_mfma_f32_16x16x32_bf16 v[102:105], v[152:155], v[184:187], v[102:105]
	v_mfma_f32_16x16x32_bf16 v[94:97], v[140:143], v[196:199], v[94:97]
	v_mfma_f32_16x16x32_bf16 v[86:89], v[152:155], v[196:199], v[86:89]
	v_mfma_f32_16x16x32_bf16 v[78:81], v[140:143], v[204:207], v[78:81]
	v_mfma_f32_16x16x32_bf16 v[70:73], v[152:155], v[204:207], v[70:73]
	v_mfma_f32_16x16x32_bf16 v[126:129], v[148:151], v[180:183], v[126:129]
	v_mfma_f32_16x16x32_bf16 v[122:125], v[156:159], v[180:183], v[122:125]
	v_mfma_f32_16x16x32_bf16 v[110:113], v[148:151], v[188:191], v[110:113]
	v_mfma_f32_16x16x32_bf16 v[102:105], v[156:159], v[188:191], v[102:105]
	v_mfma_f32_16x16x32_bf16 v[94:97], v[148:151], v[200:203], v[94:97]
	v_mfma_f32_16x16x32_bf16 v[86:89], v[156:159], v[200:203], v[86:89]
	v_mfma_f32_16x16x32_bf16 v[78:81], v[148:151], v[208:211], v[78:81]
	v_mfma_f32_16x16x32_bf16 v[70:73], v[156:159], v[208:211], v[70:73]
	s_setprio 0
	s_setprio 1
	v_mfma_f32_16x16x32_bf16 v[118:121], v[160:163], v[176:179], v[118:121]
	v_mfma_f32_16x16x32_bf16 v[114:117], v[168:171], v[176:179], v[114:117]
	v_mfma_f32_16x16x32_bf16 v[106:109], v[160:163], v[184:187], v[106:109]
	v_mfma_f32_16x16x32_bf16 v[98:101], v[168:171], v[184:187], v[98:101]
	v_mfma_f32_16x16x32_bf16 v[90:93], v[160:163], v[196:199], v[90:93]
	v_mfma_f32_16x16x32_bf16 v[82:85], v[168:171], v[196:199], v[82:85]
	v_mfma_f32_16x16x32_bf16 v[74:77], v[160:163], v[204:207], v[74:77]
	v_mfma_f32_16x16x32_bf16 v[66:69], v[168:171], v[204:207], v[66:69]
	v_mfma_f32_16x16x32_bf16 v[118:121], v[164:167], v[180:183], v[118:121]
	v_mfma_f32_16x16x32_bf16 v[114:117], v[172:175], v[180:183], v[114:117]
	v_mfma_f32_16x16x32_bf16 v[106:109], v[164:167], v[188:191], v[106:109]
	v_mfma_f32_16x16x32_bf16 v[98:101], v[172:175], v[188:191], v[98:101]
	v_mfma_f32_16x16x32_bf16 v[90:93], v[164:167], v[200:203], v[90:93]
	v_mfma_f32_16x16x32_bf16 v[82:85], v[172:175], v[200:203], v[82:85]
	v_mfma_f32_16x16x32_bf16 v[74:77], v[164:167], v[208:211], v[74:77]
	v_mfma_f32_16x16x32_bf16 v[66:69], v[172:175], v[208:211], v[66:69]
	s_setprio 0
	s_barrier
	s_mov_b32 m0, s5
	s_add_u32 s52, s26, 0x80000
	s_addc_u32 s53, s27, 0
	ds_read_b128 v[176:179], v145 offset:16384
	ds_read_b128 v[180:183], v145 offset:17408
	ds_read_b128 v[184:187], v145 offset:18432
	ds_read_b128 v[188:191], v145 offset:19456
	ds_read_b128 v[196:199], v145 offset:20480
	ds_read_b128 v[200:203], v145 offset:21504
	ds_read_b128 v[204:207], v145 offset:22528
	ds_read_b128 v[208:211], v145 offset:23552
	global_load_lds_dwordx4 v64, s[26:27]
	s_mov_b32 m0, s30
	s_nop 0
	global_load_lds_dwordx4 v130, s[26:27]
	s_mov_b32 m0, s31
	s_nop 0
	global_load_lds_dwordx4 v64, s[52:53]
	s_mov_b32 m0, s34
	s_nop 0
	global_load_lds_dwordx4 v130, s[52:53]
	s_mov_b32 m0, s2
	s_nop 0
	global_load_lds_dwordx4 v134, s[28:29]
	s_mov_b32 m0, s35
	s_nop 0
	global_load_lds_dwordx4 v132, s[28:29]
	s_waitcnt vmcnt(8)
	s_waitcnt lgkmcnt(0)
	s_barrier
	s_setprio 1
	s_waitcnt lgkmcnt(0)
	v_mfma_f32_16x16x32_bf16 v[60:63], v[140:143], v[176:179], v[60:63]
	v_mfma_f32_16x16x32_bf16 v[52:55], v[152:155], v[176:179], v[52:55]
	v_mfma_f32_16x16x32_bf16 v[44:47], v[140:143], v[184:187], v[44:47]
	v_mfma_f32_16x16x32_bf16 v[36:39], v[152:155], v[184:187], v[36:39]
	v_mfma_f32_16x16x32_bf16 v[28:31], v[140:143], v[196:199], v[28:31]
	v_mfma_f32_16x16x32_bf16 v[20:23], v[152:155], v[196:199], v[20:23]
	v_mfma_f32_16x16x32_bf16 v[12:15], v[140:143], v[204:207], v[12:15]
	v_mfma_f32_16x16x32_bf16 v[4:7], v[152:155], v[204:207], v[4:7]
	v_mfma_f32_16x16x32_bf16 v[60:63], v[148:151], v[180:183], v[60:63]
	v_mfma_f32_16x16x32_bf16 v[52:55], v[156:159], v[180:183], v[52:55]
	v_mfma_f32_16x16x32_bf16 v[44:47], v[148:151], v[188:191], v[44:47]
	v_mfma_f32_16x16x32_bf16 v[36:39], v[156:159], v[188:191], v[36:39]
	v_mfma_f32_16x16x32_bf16 v[28:31], v[148:151], v[200:203], v[28:31]
	v_mfma_f32_16x16x32_bf16 v[20:23], v[156:159], v[200:203], v[20:23]
	v_mfma_f32_16x16x32_bf16 v[12:15], v[148:151], v[208:211], v[12:15]
	v_mfma_f32_16x16x32_bf16 v[4:7], v[156:159], v[208:211], v[4:7]
	s_setprio 0
	s_setprio 1
	v_mfma_f32_16x16x32_bf16 v[56:59], v[160:163], v[176:179], v[56:59]
	v_mfma_f32_16x16x32_bf16 v[48:51], v[168:171], v[176:179], v[48:51]
	v_mfma_f32_16x16x32_bf16 v[40:43], v[160:163], v[184:187], v[40:43]
	v_mfma_f32_16x16x32_bf16 v[32:35], v[168:171], v[184:187], v[32:35]
	v_mfma_f32_16x16x32_bf16 v[24:27], v[160:163], v[196:199], v[24:27]
	v_mfma_f32_16x16x32_bf16 v[16:19], v[168:171], v[196:199], v[16:19]
	v_mfma_f32_16x16x32_bf16 v[8:11], v[160:163], v[204:207], v[8:11]
	v_mfma_f32_16x16x32_bf16 v[0:3], v[168:171], v[204:207], v[0:3]
	v_mfma_f32_16x16x32_bf16 v[56:59], v[164:167], v[180:183], v[56:59]
	v_mfma_f32_16x16x32_bf16 v[48:51], v[172:175], v[180:183], v[48:51]
	v_mfma_f32_16x16x32_bf16 v[40:43], v[164:167], v[188:191], v[40:43]
	v_mfma_f32_16x16x32_bf16 v[32:35], v[172:175], v[188:191], v[32:35]
	v_mfma_f32_16x16x32_bf16 v[24:27], v[164:167], v[200:203], v[24:27]
	v_mfma_f32_16x16x32_bf16 v[16:19], v[172:175], v[200:203], v[16:19]
	v_mfma_f32_16x16x32_bf16 v[8:11], v[164:167], v[208:211], v[8:11]
	v_mfma_f32_16x16x32_bf16 v[0:3], v[172:175], v[208:211], v[0:3]
	s_setprio 0
	s_barrier
	ds_read_b128 v[140:143], v220 offset:32768
	ds_read_b128 v[148:151], v220 offset:33792
	ds_read_b128 v[152:155], v220 offset:34816
	ds_read_b128 v[156:159], v220 offset:35840
	ds_read_b128 v[160:163], v220 offset:49152
	ds_read_b128 v[164:167], v220 offset:50176
	ds_read_b128 v[168:171], v220 offset:51200
	ds_read_b128 v[172:175], v220 offset:52224
	s_add_u32 s56, s28, 0x80000
	s_addc_u32 s57, s29, 0
	s_mov_b32 m0, s36
	ds_read_b128 v[176:179], v145 offset:32768
	ds_read_b128 v[180:183], v145 offset:33792
	ds_read_b128 v[184:187], v145 offset:34816
	ds_read_b128 v[188:191], v145 offset:35840
	ds_read_b128 v[196:199], v145 offset:36864
	ds_read_b128 v[200:203], v145 offset:37888
	ds_read_b128 v[204:207], v145 offset:38912
	ds_read_b128 v[208:211], v145 offset:39936
	global_load_lds_dwordx4 v134, s[56:57]
	s_mov_b32 m0, s37
	s_nop 0
	global_load_lds_dwordx4 v132, s[56:57]
	s_waitcnt vmcnt(8)
	s_waitcnt lgkmcnt(0)
	s_barrier
	s_setprio 1
	s_waitcnt lgkmcnt(0)
	v_mfma_f32_16x16x32_bf16 v[126:129], v[140:143], v[176:179], v[126:129]
	v_mfma_f32_16x16x32_bf16 v[122:125], v[152:155], v[176:179], v[122:125]
	v_mfma_f32_16x16x32_bf16 v[110:113], v[140:143], v[184:187], v[110:113]
	v_mfma_f32_16x16x32_bf16 v[102:105], v[152:155], v[184:187], v[102:105]
	v_mfma_f32_16x16x32_bf16 v[94:97], v[140:143], v[196:199], v[94:97]
	v_mfma_f32_16x16x32_bf16 v[86:89], v[152:155], v[196:199], v[86:89]
	v_mfma_f32_16x16x32_bf16 v[78:81], v[140:143], v[204:207], v[78:81]
	v_mfma_f32_16x16x32_bf16 v[70:73], v[152:155], v[204:207], v[70:73]
	v_mfma_f32_16x16x32_bf16 v[126:129], v[148:151], v[180:183], v[126:129]
	v_mfma_f32_16x16x32_bf16 v[122:125], v[156:159], v[180:183], v[122:125]
	v_mfma_f32_16x16x32_bf16 v[110:113], v[148:151], v[188:191], v[110:113]
	v_mfma_f32_16x16x32_bf16 v[102:105], v[156:159], v[188:191], v[102:105]
	v_mfma_f32_16x16x32_bf16 v[94:97], v[148:151], v[200:203], v[94:97]
	v_mfma_f32_16x16x32_bf16 v[86:89], v[156:159], v[200:203], v[86:89]
	v_mfma_f32_16x16x32_bf16 v[78:81], v[148:151], v[208:211], v[78:81]
	v_mfma_f32_16x16x32_bf16 v[70:73], v[156:159], v[208:211], v[70:73]
	s_setprio 0
	s_setprio 1
	v_mfma_f32_16x16x32_bf16 v[118:121], v[160:163], v[176:179], v[118:121]
	v_mfma_f32_16x16x32_bf16 v[114:117], v[168:171], v[176:179], v[114:117]
	v_mfma_f32_16x16x32_bf16 v[106:109], v[160:163], v[184:187], v[106:109]
	v_mfma_f32_16x16x32_bf16 v[98:101], v[168:171], v[184:187], v[98:101]
	v_mfma_f32_16x16x32_bf16 v[90:93], v[160:163], v[196:199], v[90:93]
	v_mfma_f32_16x16x32_bf16 v[82:85], v[168:171], v[196:199], v[82:85]
	v_mfma_f32_16x16x32_bf16 v[74:77], v[160:163], v[204:207], v[74:77]
	v_mfma_f32_16x16x32_bf16 v[66:69], v[168:171], v[204:207], v[66:69]
	v_mfma_f32_16x16x32_bf16 v[118:121], v[164:167], v[180:183], v[118:121]
	v_mfma_f32_16x16x32_bf16 v[114:117], v[172:175], v[180:183], v[114:117]
	v_mfma_f32_16x16x32_bf16 v[106:109], v[164:167], v[188:191], v[106:109]
	v_mfma_f32_16x16x32_bf16 v[98:101], v[172:175], v[188:191], v[98:101]
	v_mfma_f32_16x16x32_bf16 v[90:93], v[164:167], v[200:203], v[90:93]
	v_mfma_f32_16x16x32_bf16 v[82:85], v[172:175], v[200:203], v[82:85]
	v_mfma_f32_16x16x32_bf16 v[74:77], v[164:167], v[208:211], v[74:77]
	v_mfma_f32_16x16x32_bf16 v[66:69], v[172:175], v[208:211], v[66:69]
	s_setprio 0
	s_barrier
	s_add_i32 m0, s38, 0xffffff80
	s_add_u32 s58, s26, 0x80080
	s_addc_u32 s59, s27, 0
	ds_read_b128 v[176:179], v145 offset:49152
	ds_read_b128 v[180:183], v145 offset:50176
	ds_read_b128 v[184:187], v145 offset:51200
	ds_read_b128 v[188:191], v145 offset:52224
	ds_read_b128 v[196:199], v145 offset:53248
	ds_read_b128 v[200:203], v145 offset:54272
	ds_read_b128 v[204:207], v145 offset:55296
	ds_read_b128 v[208:211], v145 offset:56320
	global_load_lds_dwordx4 v64, s[26:27] offset:128
	s_add_i32 m0, s39, 0xffffff80
	s_nop 0
	global_load_lds_dwordx4 v130, s[26:27] offset:128
	s_mov_b32 m0, s42
	s_nop 0
	global_load_lds_dwordx4 v64, s[58:59]
	s_mov_b32 m0, s43
	s_nop 0
	global_load_lds_dwordx4 v130, s[58:59]
	s_add_i32 m0, s40, 0xffffff80
	s_nop 0
	global_load_lds_dwordx4 v134, s[28:29] offset:128
	s_add_i32 m0, s41, 0xffffff80
	s_nop 0
	global_load_lds_dwordx4 v132, s[28:29] offset:128
	s_waitcnt vmcnt(8)
	s_waitcnt lgkmcnt(0)
	s_barrier
	s_setprio 1
	s_waitcnt lgkmcnt(0)
	v_mfma_f32_16x16x32_bf16 v[60:63], v[140:143], v[176:179], v[60:63]
	v_mfma_f32_16x16x32_bf16 v[52:55], v[152:155], v[176:179], v[52:55]
	v_mfma_f32_16x16x32_bf16 v[44:47], v[140:143], v[184:187], v[44:47]
	v_mfma_f32_16x16x32_bf16 v[36:39], v[152:155], v[184:187], v[36:39]
	v_mfma_f32_16x16x32_bf16 v[28:31], v[140:143], v[196:199], v[28:31]
	v_mfma_f32_16x16x32_bf16 v[20:23], v[152:155], v[196:199], v[20:23]
	v_mfma_f32_16x16x32_bf16 v[12:15], v[140:143], v[204:207], v[12:15]
	v_mfma_f32_16x16x32_bf16 v[4:7], v[152:155], v[204:207], v[4:7]
	v_mfma_f32_16x16x32_bf16 v[60:63], v[148:151], v[180:183], v[60:63]
	v_mfma_f32_16x16x32_bf16 v[52:55], v[156:159], v[180:183], v[52:55]
	v_mfma_f32_16x16x32_bf16 v[44:47], v[148:151], v[188:191], v[44:47]
	v_mfma_f32_16x16x32_bf16 v[36:39], v[156:159], v[188:191], v[36:39]
	v_mfma_f32_16x16x32_bf16 v[28:31], v[148:151], v[200:203], v[28:31]
	v_mfma_f32_16x16x32_bf16 v[20:23], v[156:159], v[200:203], v[20:23]
	v_mfma_f32_16x16x32_bf16 v[12:15], v[148:151], v[208:211], v[12:15]
	v_mfma_f32_16x16x32_bf16 v[4:7], v[156:159], v[208:211], v[4:7]
	s_setprio 0
	s_setprio 1
	v_mfma_f32_16x16x32_bf16 v[56:59], v[160:163], v[176:179], v[56:59]
	v_mfma_f32_16x16x32_bf16 v[48:51], v[168:171], v[176:179], v[48:51]
	v_mfma_f32_16x16x32_bf16 v[40:43], v[160:163], v[184:187], v[40:43]
	v_mfma_f32_16x16x32_bf16 v[32:35], v[168:171], v[184:187], v[32:35]
	v_mfma_f32_16x16x32_bf16 v[24:27], v[160:163], v[196:199], v[24:27]
	v_mfma_f32_16x16x32_bf16 v[16:19], v[168:171], v[196:199], v[16:19]
	v_mfma_f32_16x16x32_bf16 v[8:11], v[160:163], v[204:207], v[8:11]
	v_mfma_f32_16x16x32_bf16 v[0:3], v[168:171], v[204:207], v[0:3]
	v_mfma_f32_16x16x32_bf16 v[56:59], v[164:167], v[180:183], v[56:59]
	v_mfma_f32_16x16x32_bf16 v[48:51], v[172:175], v[180:183], v[48:51]
	v_mfma_f32_16x16x32_bf16 v[40:43], v[164:167], v[188:191], v[40:43]
	v_mfma_f32_16x16x32_bf16 v[32:35], v[172:175], v[188:191], v[32:35]
	v_mfma_f32_16x16x32_bf16 v[24:27], v[164:167], v[200:203], v[24:27]
	v_mfma_f32_16x16x32_bf16 v[16:19], v[172:175], v[200:203], v[16:19]
	v_mfma_f32_16x16x32_bf16 v[8:11], v[164:167], v[208:211], v[8:11]
	v_mfma_f32_16x16x32_bf16 v[0:3], v[172:175], v[208:211], v[0:3]
	s_setprio 0
	s_barrier
	s_add_i32 s51, s51, 2
	s_add_u32 s24, s24, 0x100
	s_addc_u32 s25, s25, 0
	s_add_u32 s49, s49, 0x100
	s_addc_u32 s50, s50, 0
	s_cmp_gt_u32 s51, 29
	s_cbranch_scc0 .LBB0_170
	s_and_b64 vcc, exec, s[10:11]
	s_cbranch_vccz .LBB0_173
	s_barrier

.LBB0_187:
	s_add_i32 s23, s91, -8
	s_cmp_lt_u32 s23, -13
	s_cselect_b64 s[8:9], -1, 0
	s_or_b64 s[24:25], s[8:9], s[6:7]
	s_cmp_lt_u32 s23, 7
	s_cselect_b64 s[8:9], -1, 0
	s_and_b64 s[6:7], s[8:9], s[6:7]
	s_xor_b64 s[8:9], s[6:7], -1
	s_and_b64 s[24:25], s[24:25], exec
	v_readlane_b32 s36, v254, 45
	s_cselect_b32 s25, 0, s57
	s_cselect_b32 s24, 0, s56
	s_cselect_b32 s27, s81, 0
	s_cselect_b32 s26, s80, 0
	s_and_b64 s[28:29], s[6:7], exec
	v_readlane_b32 s42, v254, 51
	v_readlane_b32 s43, v254, 52
	v_readlane_b32 s30, v254, 56
	s_cselect_b32 s29, s43, 0
	s_cselect_b32 s28, s42, 0
	s_lshl_b32 s23, s30, 1
	v_readlane_b32 s31, v254, 57
	s_add_i32 s30, s16, s23
	s_ashr_i32 s31, s30, 31
	s_lshl_b64 s[30:31], s[30:31], 16
	v_readlane_b32 s34, v254, 54
	v_readlane_b32 s35, v254, 55
	s_add_u32 s16, s34, s30
	s_addc_u32 s23, s35, s31
	s_and_b64 s[6:7], s[6:7], exec
	s_cselect_b32 s31, 0, s23
	s_cselect_b32 s30, 0, s16
	s_add_i32 s78, s5, 0x18000
	v_and_b32_e32 v18, 15, v194
	v_lshl_add_u64 v[0:1], v[0:1], 0, s[98:99]
	s_mov_b32 m0, s78
	s_add_i32 s79, s5, 0x1a000
	v_lshl_or_b32 v195, s22, 6, v18
	s_lshl_b32 s6, s22, 13
	s_waitcnt vmcnt(2)
	s_barrier
	global_load_lds_dwordx4 v[0:1], off
	v_lshl_add_u64 v[0:1], v[2:3], 0, s[98:99]
	s_mov_b32 m0, s79
	s_add_i32 s22, s5, 0x8000
	global_load_lds_dwordx4 v[0:1], off
	v_lshl_add_u64 v[0:1], v[8:9], 0, s[98:99]
	s_mov_b32 m0, s22
	s_add_i32 s23, s5, 0xa000
	global_load_lds_dwordx4 v[0:1], off
	v_lshl_add_u64 v[0:1], v[10:11], 0, s[98:99]
	s_mov_b32 m0, s23
	s_add_i32 s50, s5, 0x1c000
	global_load_lds_dwordx4 v[0:1], off
	v_lshl_add_u64 v[0:1], v[4:5], 0, s[98:99]
	s_mov_b32 m0, s50
	s_add_i32 s51, s5, 0x1e000
	global_load_lds_dwordx4 v[0:1], off
	v_lshl_add_u64 v[0:1], v[6:7], 0, s[98:99]
	s_mov_b32 m0, s51
	v_bfe_u32 v19, v194, 4, 2
	global_load_lds_dwordx4 v[0:1], off
	v_lshlrev_b32_e32 v20, 4, v19
	v_lshl_or_b32 v18, v18, 6, v20
	v_lshlrev_b32_e32 v20, 2, v194
	v_and_b32_e32 v20, 32, v20
	v_bitop3_b32 v241, v18, s6, v20 bitop3:0xde
	s_lshl_b32 s6, s17, 5
	s_and_b32 s16, s6, 0x60
	s_lshr_b32 s72, s14, 6
	s_lshl_b32 s6, s16, 7
	s_add_i32 s73, s72, -2
	s_cmpk_lt_u32 s15, 0x100
	v_readlane_b32 s37, v254, 46
	s_cselect_b64 s[34:35], -1, 0
	s_cmp_lg_u64 s[24:25], 0
	v_readlane_b32 s38, v254, 47
	v_readlane_b32 s39, v254, 48
	s_cselect_b64 s[36:37], -1, 0
	s_cmp_lg_u64 s[28:29], 0
	s_cselect_b64 s[38:39], -1, 0
	s_cmp_lg_u64 s[94:95], 0
	v_add_u32_e32 v0, v17, v15
	v_readlane_b32 s40, v254, 49
	v_readlane_b32 s41, v254, 50
	s_cselect_b64 s[14:15], -1, 0
	v_add_lshl_u32 v0, v0, v16, 1
	v_mov_b32_e32 v1, v65
	s_waitcnt vmcnt(6)
	s_and_b64 s[40:41], s[8:9], s[14:15]
	v_lshl_add_u64 v[202:203], s[92:93], 0, v[0:1]
	v_add_u32_e32 v0, v14, v12
	s_cmp_lg_u64 s[30:31], 0
	v_add_lshl_u32 v0, v0, v13, 1
	s_mov_b32 s91, 0
	v_bitop3_b32 v242, s6, v18, v20 bitop3:0xf6
	v_cmp_eq_u32_e64 s[6:7], 0, v19
	s_cselect_b64 s[42:43], -1, 0
	v_lshl_or_b32 v243, v19, 3, s16
	v_lshl_add_u64 v[204:205], s[92:93], 0, v[0:1]
	v_readlane_b32 s16, v254, 22
	v_readlane_b32 s17, v254, 21
	s_barrier
	v_add_u32_e32 v252, 0x10000, v242
	s_branch .LBB0_190

.LBB0_201:
	s_add_i32 s48, s12, 2
	ds_read_b128 v[130:133], v252
	ds_read_b128 v[134:137], v252 offset:1024
	ds_read_b128 v[138:141], v252 offset:2048
	ds_read_b128 v[142:145], v252 offset:3072
	ds_read_b128 v[146:149], v252 offset:16384
	ds_read_b128 v[150:153], v252 offset:17408
	ds_read_b128 v[154:157], v252 offset:18432
	ds_read_b128 v[158:161], v252 offset:19456
	s_add_u32 s49, s10, 0x80
	s_addc_u32 s13, s11, 0
	s_cmp_eq_u32 s73, s12
	s_cselect_b32 s12, s44, s49
	s_cselect_b32 s13, s45, s13
	s_cselect_b32 s77, s47, s15
	s_cselect_b32 s76, s46, s14
	s_add_i32 m0, s5, 0xc000
	ds_read_b128 v[162:165], v241
	ds_read_b128 v[166:169], v241 offset:1024
	ds_read_b128 v[170:173], v241 offset:2048
	ds_read_b128 v[174:177], v241 offset:3072
	ds_read_b128 v[178:181], v241 offset:4096
	ds_read_b128 v[182:185], v241 offset:5120
	ds_read_b128 v[186:189], v241 offset:6144
	ds_read_b128 v[190:193], v241 offset:7168
	global_load_lds_dwordx4 v202, s[10:11]
	s_add_i32 m0, s5, 0xe000
	s_nop 0
	global_load_lds_dwordx4 v204, s[10:11]
	s_waitcnt vmcnt(8)
	s_waitcnt lgkmcnt(0)
	s_barrier
	s_setprio 1
	s_waitcnt lgkmcnt(0)
	v_mfma_f32_16x16x32_bf16 v[126:129], v[130:133], v[162:165], v[126:129]
	v_mfma_f32_16x16x32_bf16 v[122:125], v[138:141], v[162:165], v[122:125]
	v_mfma_f32_16x16x32_bf16 v[110:113], v[130:133], v[170:173], v[110:113]
	v_mfma_f32_16x16x32_bf16 v[106:109], v[138:141], v[170:173], v[106:109]
	v_mfma_f32_16x16x32_bf16 v[94:97], v[130:133], v[178:181], v[94:97]
	v_mfma_f32_16x16x32_bf16 v[90:93], v[138:141], v[178:181], v[90:93]
	v_mfma_f32_16x16x32_bf16 v[78:81], v[130:133], v[186:189], v[78:81]
	v_mfma_f32_16x16x32_bf16 v[74:77], v[138:141], v[186:189], v[74:77]
	v_mfma_f32_16x16x32_bf16 v[126:129], v[134:137], v[166:169], v[126:129]
	v_mfma_f32_16x16x32_bf16 v[122:125], v[142:145], v[166:169], v[122:125]
	v_mfma_f32_16x16x32_bf16 v[110:113], v[134:137], v[174:177], v[110:113]
	v_mfma_f32_16x16x32_bf16 v[106:109], v[142:145], v[174:177], v[106:109]
	v_mfma_f32_16x16x32_bf16 v[94:97], v[134:137], v[182:185], v[94:97]
	v_mfma_f32_16x16x32_bf16 v[90:93], v[142:145], v[182:185], v[90:93]
	v_mfma_f32_16x16x32_bf16 v[78:81], v[134:137], v[190:193], v[78:81]
	v_mfma_f32_16x16x32_bf16 v[74:77], v[142:145], v[190:193], v[74:77]
	s_setprio 0
	s_setprio 1
	v_mfma_f32_16x16x32_bf16 v[118:121], v[146:149], v[162:165], v[118:121]
	v_mfma_f32_16x16x32_bf16 v[114:117], v[154:157], v[162:165], v[114:117]
	v_mfma_f32_16x16x32_bf16 v[102:105], v[146:149], v[170:173], v[102:105]
	v_mfma_f32_16x16x32_bf16 v[98:101], v[154:157], v[170:173], v[98:101]
	v_mfma_f32_16x16x32_bf16 v[86:89], v[146:149], v[178:181], v[86:89]
	v_mfma_f32_16x16x32_bf16 v[82:85], v[154:157], v[178:181], v[82:85]
	v_mfma_f32_16x16x32_bf16 v[70:73], v[146:149], v[186:189], v[70:73]
	v_mfma_f32_16x16x32_bf16 v[66:69], v[154:157], v[186:189], v[66:69]
	v_mfma_f32_16x16x32_bf16 v[118:121], v[150:153], v[166:169], v[118:121]
	v_mfma_f32_16x16x32_bf16 v[114:117], v[158:161], v[166:169], v[114:117]
	v_mfma_f32_16x16x32_bf16 v[102:105], v[150:153], v[174:177], v[102:105]
	v_mfma_f32_16x16x32_bf16 v[98:101], v[158:161], v[174:177], v[98:101]
	v_mfma_f32_16x16x32_bf16 v[86:89], v[150:153], v[182:185], v[86:89]
	v_mfma_f32_16x16x32_bf16 v[82:85], v[158:161], v[182:185], v[82:85]
	v_mfma_f32_16x16x32_bf16 v[70:73], v[150:153], v[190:193], v[70:73]
	v_mfma_f32_16x16x32_bf16 v[66:69], v[158:161], v[190:193], v[66:69]
	s_setprio 0
	s_barrier
	s_mov_b32 m0, s52
	s_add_u32 s58, s76, s0
	s_addc_u32 s59, s77, 0
	ds_read_b128 v[162:165], v241 offset:16384
	ds_read_b128 v[166:169], v241 offset:17408
	ds_read_b128 v[170:173], v241 offset:18432
	ds_read_b128 v[174:177], v241 offset:19456
	ds_read_b128 v[178:181], v241 offset:20480
	ds_read_b128 v[182:185], v241 offset:21504
	ds_read_b128 v[186:189], v241 offset:22528
	ds_read_b128 v[190:193], v241 offset:23552
	global_load_lds_dwordx4 v64, s[76:77]
	s_mov_b32 m0, s53
	s_nop 0
	global_load_lds_dwordx4 v196, s[76:77]
	s_mov_b32 m0, s54
	s_nop 0
	global_load_lds_dwordx4 v64, s[58:59]
	s_mov_b32 m0, s55
	s_nop 0
	global_load_lds_dwordx4 v196, s[58:59]
	s_mov_b32 m0, s5
	s_nop 0
	global_load_lds_dwordx4 v200, s[12:13]
	s_mov_b32 m0, s87
	s_nop 0
	global_load_lds_dwordx4 v198, s[12:13]
	s_waitcnt vmcnt(8)
	s_waitcnt lgkmcnt(0)
	s_barrier
	s_setprio 1
	s_waitcnt lgkmcnt(0)
	v_mfma_f32_16x16x32_bf16 v[60:63], v[130:133], v[162:165], v[60:63]
	v_mfma_f32_16x16x32_bf16 v[56:59], v[138:141], v[162:165], v[56:59]
	v_mfma_f32_16x16x32_bf16 v[44:47], v[130:133], v[170:173], v[44:47]
	v_mfma_f32_16x16x32_bf16 v[40:43], v[138:141], v[170:173], v[40:43]
	v_mfma_f32_16x16x32_bf16 v[28:31], v[130:133], v[178:181], v[28:31]
	v_mfma_f32_16x16x32_bf16 v[24:27], v[138:141], v[178:181], v[24:27]
	v_mfma_f32_16x16x32_bf16 v[12:15], v[130:133], v[186:189], v[12:15]
	v_mfma_f32_16x16x32_bf16 v[8:11], v[138:141], v[186:189], v[8:11]
	v_mfma_f32_16x16x32_bf16 v[60:63], v[134:137], v[166:169], v[60:63]
	v_mfma_f32_16x16x32_bf16 v[56:59], v[142:145], v[166:169], v[56:59]
	v_mfma_f32_16x16x32_bf16 v[44:47], v[134:137], v[174:177], v[44:47]
	v_mfma_f32_16x16x32_bf16 v[40:43], v[142:145], v[174:177], v[40:43]
	v_mfma_f32_16x16x32_bf16 v[28:31], v[134:137], v[182:185], v[28:31]
	v_mfma_f32_16x16x32_bf16 v[24:27], v[142:145], v[182:185], v[24:27]
	v_mfma_f32_16x16x32_bf16 v[12:15], v[134:137], v[190:193], v[12:15]
	v_mfma_f32_16x16x32_bf16 v[8:11], v[142:145], v[190:193], v[8:11]
	s_setprio 0
	s_setprio 1
	v_mfma_f32_16x16x32_bf16 v[52:55], v[146:149], v[162:165], v[52:55]
	v_mfma_f32_16x16x32_bf16 v[48:51], v[154:157], v[162:165], v[48:51]
	v_mfma_f32_16x16x32_bf16 v[36:39], v[146:149], v[170:173], v[36:39]
	v_mfma_f32_16x16x32_bf16 v[32:35], v[154:157], v[170:173], v[32:35]
	v_mfma_f32_16x16x32_bf16 v[20:23], v[146:149], v[178:181], v[20:23]
	v_mfma_f32_16x16x32_bf16 v[16:19], v[154:157], v[178:181], v[16:19]
	v_mfma_f32_16x16x32_bf16 v[4:7], v[146:149], v[186:189], v[4:7]
	v_mfma_f32_16x16x32_bf16 v[0:3], v[154:157], v[186:189], v[0:3]
	v_mfma_f32_16x16x32_bf16 v[52:55], v[150:153], v[166:169], v[52:55]
	v_mfma_f32_16x16x32_bf16 v[48:51], v[158:161], v[166:169], v[48:51]
	v_mfma_f32_16x16x32_bf16 v[36:39], v[150:153], v[174:177], v[36:39]
	v_mfma_f32_16x16x32_bf16 v[32:35], v[158:161], v[174:177], v[32:35]
	v_mfma_f32_16x16x32_bf16 v[20:23], v[150:153], v[182:185], v[20:23]
	v_mfma_f32_16x16x32_bf16 v[16:19], v[158:161], v[182:185], v[16:19]
	v_mfma_f32_16x16x32_bf16 v[4:7], v[150:153], v[190:193], v[4:7]
	v_mfma_f32_16x16x32_bf16 v[0:3], v[158:161], v[190:193], v[0:3]
	s_setprio 0
	s_barrier
	ds_read_b128 v[130:133], v252 offset:32768
	ds_read_b128 v[134:137], v252 offset:33792
	ds_read_b128 v[138:141], v252 offset:34816
	ds_read_b128 v[142:145], v252 offset:35840
	ds_read_b128 v[146:149], v252 offset:49152
	ds_read_b128 v[150:153], v252 offset:50176
	ds_read_b128 v[154:157], v252 offset:51200
	ds_read_b128 v[158:161], v252 offset:52224
	s_add_u32 s60, s12, s92
	s_addc_u32 s61, s13, 0
	s_mov_b32 m0, s88
	ds_read_b128 v[162:165], v241 offset:32768
	ds_read_b128 v[166:169], v241 offset:33792
	ds_read_b128 v[170:173], v241 offset:34816
	ds_read_b128 v[174:177], v241 offset:35840
	ds_read_b128 v[178:181], v241 offset:36864
	ds_read_b128 v[182:185], v241 offset:37888
	ds_read_b128 v[186:189], v241 offset:38912
	ds_read_b128 v[190:193], v241 offset:39936
	global_load_lds_dwordx4 v200, s[60:61]
	s_mov_b32 m0, s90
	s_nop 0
	global_load_lds_dwordx4 v198, s[60:61]
	s_waitcnt vmcnt(8)
	s_waitcnt lgkmcnt(0)
	s_barrier
	s_setprio 1
	s_waitcnt lgkmcnt(0)
	v_mfma_f32_16x16x32_bf16 v[126:129], v[130:133], v[162:165], v[126:129]
	v_mfma_f32_16x16x32_bf16 v[122:125], v[138:141], v[162:165], v[122:125]
	v_mfma_f32_16x16x32_bf16 v[110:113], v[130:133], v[170:173], v[110:113]
	v_mfma_f32_16x16x32_bf16 v[106:109], v[138:141], v[170:173], v[106:109]
	v_mfma_f32_16x16x32_bf16 v[94:97], v[130:133], v[178:181], v[94:97]
	v_mfma_f32_16x16x32_bf16 v[90:93], v[138:141], v[178:181], v[90:93]
	v_mfma_f32_16x16x32_bf16 v[78:81], v[130:133], v[186:189], v[78:81]
	v_mfma_f32_16x16x32_bf16 v[74:77], v[138:141], v[186:189], v[74:77]
	v_mfma_f32_16x16x32_bf16 v[126:129], v[134:137], v[166:169], v[126:129]
	v_mfma_f32_16x16x32_bf16 v[122:125], v[142:145], v[166:169], v[122:125]
	v_mfma_f32_16x16x32_bf16 v[110:113], v[134:137], v[174:177], v[110:113]
	v_mfma_f32_16x16x32_bf16 v[106:109], v[142:145], v[174:177], v[106:109]
	v_mfma_f32_16x16x32_bf16 v[94:97], v[134:137], v[182:185], v[94:97]
	v_mfma_f32_16x16x32_bf16 v[90:93], v[142:145], v[182:185], v[90:93]
	v_mfma_f32_16x16x32_bf16 v[78:81], v[134:137], v[190:193], v[78:81]
	v_mfma_f32_16x16x32_bf16 v[74:77], v[142:145], v[190:193], v[74:77]
	s_setprio 0
	s_setprio 1
	v_mfma_f32_16x16x32_bf16 v[118:121], v[146:149], v[162:165], v[118:121]
	v_mfma_f32_16x16x32_bf16 v[114:117], v[154:157], v[162:165], v[114:117]
	v_mfma_f32_16x16x32_bf16 v[102:105], v[146:149], v[170:173], v[102:105]
	v_mfma_f32_16x16x32_bf16 v[98:101], v[154:157], v[170:173], v[98:101]
	v_mfma_f32_16x16x32_bf16 v[86:89], v[146:149], v[178:181], v[86:89]
	v_mfma_f32_16x16x32_bf16 v[82:85], v[154:157], v[178:181], v[82:85]
	v_mfma_f32_16x16x32_bf16 v[70:73], v[146:149], v[186:189], v[70:73]
	v_mfma_f32_16x16x32_bf16 v[66:69], v[154:157], v[186:189], v[66:69]
	v_mfma_f32_16x16x32_bf16 v[118:121], v[150:153], v[166:169], v[118:121]
	v_mfma_f32_16x16x32_bf16 v[114:117], v[158:161], v[166:169], v[114:117]
	v_mfma_f32_16x16x32_bf16 v[102:105], v[150:153], v[174:177], v[102:105]
	v_mfma_f32_16x16x32_bf16 v[98:101], v[158:161], v[174:177], v[98:101]
	v_mfma_f32_16x16x32_bf16 v[86:89], v[150:153], v[182:185], v[86:89]
	v_mfma_f32_16x16x32_bf16 v[82:85], v[158:161], v[182:185], v[82:85]
	v_mfma_f32_16x16x32_bf16 v[70:73], v[150:153], v[190:193], v[70:73]
	v_mfma_f32_16x16x32_bf16 v[66:69], v[158:161], v[190:193], v[66:69]
	s_setprio 0
	s_barrier
	s_add_i32 m0, s78, 0xffffff80
	ds_read_b128 v[162:165], v241 offset:49152
	ds_read_b128 v[166:169], v241 offset:50176
	ds_read_b128 v[170:173], v241 offset:51200
	ds_read_b128 v[174:177], v241 offset:52224
	ds_read_b128 v[178:181], v241 offset:53248
	ds_read_b128 v[182:185], v241 offset:54272
	ds_read_b128 v[186:189], v241 offset:55296
	ds_read_b128 v[190:193], v241 offset:56320
	global_load_lds_dwordx4 v64, s[76:77] offset:128
	s_add_i32 m0, s79, 0xffffff80
	s_nop 0
	global_load_lds_dwordx4 v196, s[76:77] offset:128
	s_add_i32 m0, s50, 0xffffff80
	s_nop 0
	global_load_lds_dwordx4 v64, s[58:59] offset:128
	s_add_i32 m0, s51, 0xffffff80
	s_nop 0
	global_load_lds_dwordx4 v196, s[58:59] offset:128
	s_add_i32 m0, s22, 0xffffff80
	s_nop 0
	global_load_lds_dwordx4 v200, s[12:13] offset:128
	s_add_i32 m0, s23, 0xffffff80
	s_nop 0
	global_load_lds_dwordx4 v198, s[12:13] offset:128
	s_waitcnt vmcnt(8)
	s_waitcnt lgkmcnt(0)
	s_barrier
	s_setprio 1
	s_waitcnt lgkmcnt(0)
	v_mfma_f32_16x16x32_bf16 v[60:63], v[130:133], v[162:165], v[60:63]
	v_mfma_f32_16x16x32_bf16 v[56:59], v[138:141], v[162:165], v[56:59]
	v_mfma_f32_16x16x32_bf16 v[44:47], v[130:133], v[170:173], v[44:47]
	v_mfma_f32_16x16x32_bf16 v[40:43], v[138:141], v[170:173], v[40:43]
	v_mfma_f32_16x16x32_bf16 v[28:31], v[130:133], v[178:181], v[28:31]
	v_mfma_f32_16x16x32_bf16 v[24:27], v[138:141], v[178:181], v[24:27]
	v_mfma_f32_16x16x32_bf16 v[12:15], v[130:133], v[186:189], v[12:15]
	v_mfma_f32_16x16x32_bf16 v[8:11], v[138:141], v[186:189], v[8:11]
	v_mfma_f32_16x16x32_bf16 v[60:63], v[134:137], v[166:169], v[60:63]
	v_mfma_f32_16x16x32_bf16 v[56:59], v[142:145], v[166:169], v[56:59]
	v_mfma_f32_16x16x32_bf16 v[44:47], v[134:137], v[174:177], v[44:47]
	v_mfma_f32_16x16x32_bf16 v[40:43], v[142:145], v[174:177], v[40:43]
	v_mfma_f32_16x16x32_bf16 v[28:31], v[134:137], v[182:185], v[28:31]
	v_mfma_f32_16x16x32_bf16 v[24:27], v[142:145], v[182:185], v[24:27]
	v_mfma_f32_16x16x32_bf16 v[12:15], v[134:137], v[190:193], v[12:15]
	v_mfma_f32_16x16x32_bf16 v[8:11], v[142:145], v[190:193], v[8:11]
	s_setprio 0
	s_setprio 1
	v_mfma_f32_16x16x32_bf16 v[52:55], v[146:149], v[162:165], v[52:55]
	v_mfma_f32_16x16x32_bf16 v[48:51], v[154:157], v[162:165], v[48:51]
	v_mfma_f32_16x16x32_bf16 v[36:39], v[146:149], v[170:173], v[36:39]
	v_mfma_f32_16x16x32_bf16 v[32:35], v[154:157], v[170:173], v[32:35]
	v_mfma_f32_16x16x32_bf16 v[20:23], v[146:149], v[178:181], v[20:23]
	v_mfma_f32_16x16x32_bf16 v[16:19], v[154:157], v[178:181], v[16:19]
	v_mfma_f32_16x16x32_bf16 v[4:7], v[146:149], v[186:189], v[4:7]
	v_mfma_f32_16x16x32_bf16 v[0:3], v[154:157], v[186:189], v[0:3]
	v_mfma_f32_16x16x32_bf16 v[52:55], v[150:153], v[166:169], v[52:55]
	v_mfma_f32_16x16x32_bf16 v[48:51], v[158:161], v[166:169], v[48:51]
	v_mfma_f32_16x16x32_bf16 v[36:39], v[150:153], v[174:177], v[36:39]
	v_mfma_f32_16x16x32_bf16 v[32:35], v[158:161], v[174:177], v[32:35]
	v_mfma_f32_16x16x32_bf16 v[20:23], v[150:153], v[182:185], v[20:23]
	v_mfma_f32_16x16x32_bf16 v[16:19], v[158:161], v[182:185], v[16:19]
	v_mfma_f32_16x16x32_bf16 v[4:7], v[150:153], v[190:193], v[4:7]
	v_mfma_f32_16x16x32_bf16 v[0:3], v[158:161], v[190:193], v[0:3]
	s_setprio 0
	s_barrier
	s_add_u32 s10, s10, 0x100
	s_addc_u32 s11, s11, 0
	s_add_u32 s14, s14, 0x100
	s_addc_u32 s15, s15, 0
	s_cmp_ge_u32 s48, s72
	s_mov_b32 s12, s48
	s_cbranch_scc0 .LBB0_201
	s_and_b64 vcc, exec, s[34:35]
	s_cbranch_vccz .LBB0_204
	s_barrier

.LBB0_323:
	ds_read_b128 v[130:133], v241
	ds_read_b128 v[134:137], v241 offset:1024
	ds_read_b128 v[138:141], v241 offset:2048
	ds_read_b128 v[142:145], v241 offset:3072
	ds_read_b128 v[156:159], v241 offset:16384
	ds_read_b128 v[160:163], v241 offset:17408
	ds_read_b128 v[164:167], v241 offset:18432
	ds_read_b128 v[168:171], v241 offset:19456
	s_add_u32 s28, s10, 0xfff80080
	s_addc_u32 s29, s11, -1
	s_cmp_eq_u32 s74, 28
	s_cselect_b32 s31, s1, s29
	s_cselect_b32 s30, s34, s28
	s_cselect_b32 s29, s21, s73
	s_cselect_b32 s28, s35, s72
	s_add_i32 m0, s36, 0xc000
	ds_read_b128 v[172:175], v179
	ds_read_b128 v[202:205], v179 offset:1024
	ds_read_b128 v[206:209], v179 offset:2048
	ds_read_b128 v[210:213], v179 offset:3072
	ds_read_b128 v[214:217], v179 offset:4096
	ds_read_b128 v[218:221], v179 offset:5120
	ds_read_b128 v[222:225], v179 offset:6144
	ds_read_b128 v[242:245], v179 offset:7168
	global_load_lds_dwordx4 v152, s[10:11]
	s_add_i32 m0, s36, 0xe000
	s_nop 0
	global_load_lds_dwordx4 v154, s[10:11]
	s_waitcnt vmcnt(8)
	s_waitcnt lgkmcnt(0)
	s_barrier
	s_setprio 1
	s_waitcnt lgkmcnt(0)
	v_mfma_f32_16x16x32_bf16 v[126:129], v[130:133], v[172:175], v[126:129]
	v_mfma_f32_16x16x32_bf16 v[122:125], v[138:141], v[172:175], v[122:125]
	v_mfma_f32_16x16x32_bf16 v[110:113], v[130:133], v[206:209], v[110:113]
	v_mfma_f32_16x16x32_bf16 v[106:109], v[138:141], v[206:209], v[106:109]
	v_mfma_f32_16x16x32_bf16 v[94:97], v[130:133], v[214:217], v[94:97]
	v_mfma_f32_16x16x32_bf16 v[90:93], v[138:141], v[214:217], v[90:93]
	v_mfma_f32_16x16x32_bf16 v[78:81], v[130:133], v[222:225], v[78:81]
	v_mfma_f32_16x16x32_bf16 v[74:77], v[138:141], v[222:225], v[74:77]
	v_mfma_f32_16x16x32_bf16 v[126:129], v[134:137], v[202:205], v[126:129]
	v_mfma_f32_16x16x32_bf16 v[122:125], v[142:145], v[202:205], v[122:125]
	v_mfma_f32_16x16x32_bf16 v[110:113], v[134:137], v[210:213], v[110:113]
	v_mfma_f32_16x16x32_bf16 v[106:109], v[142:145], v[210:213], v[106:109]
	v_mfma_f32_16x16x32_bf16 v[94:97], v[134:137], v[218:221], v[94:97]
	v_mfma_f32_16x16x32_bf16 v[90:93], v[142:145], v[218:221], v[90:93]
	v_mfma_f32_16x16x32_bf16 v[78:81], v[134:137], v[242:245], v[78:81]
	v_mfma_f32_16x16x32_bf16 v[74:77], v[142:145], v[242:245], v[74:77]
	s_setprio 0
	s_setprio 1
	v_mfma_f32_16x16x32_bf16 v[118:121], v[156:159], v[172:175], v[118:121]
	v_mfma_f32_16x16x32_bf16 v[114:117], v[164:167], v[172:175], v[114:117]
	v_mfma_f32_16x16x32_bf16 v[102:105], v[156:159], v[206:209], v[102:105]
	v_mfma_f32_16x16x32_bf16 v[98:101], v[164:167], v[206:209], v[98:101]
	v_mfma_f32_16x16x32_bf16 v[86:89], v[156:159], v[214:217], v[86:89]
	v_mfma_f32_16x16x32_bf16 v[82:85], v[164:167], v[214:217], v[82:85]
	v_mfma_f32_16x16x32_bf16 v[70:73], v[156:159], v[222:225], v[70:73]
	v_mfma_f32_16x16x32_bf16 v[66:69], v[164:167], v[222:225], v[66:69]
	v_mfma_f32_16x16x32_bf16 v[118:121], v[160:163], v[202:205], v[118:121]
	v_mfma_f32_16x16x32_bf16 v[114:117], v[168:171], v[202:205], v[114:117]
	v_mfma_f32_16x16x32_bf16 v[102:105], v[160:163], v[210:213], v[102:105]
	v_mfma_f32_16x16x32_bf16 v[98:101], v[168:171], v[210:213], v[98:101]
	v_mfma_f32_16x16x32_bf16 v[86:89], v[160:163], v[218:221], v[86:89]
	v_mfma_f32_16x16x32_bf16 v[82:85], v[168:171], v[218:221], v[82:85]
	v_mfma_f32_16x16x32_bf16 v[70:73], v[160:163], v[242:245], v[70:73]
	v_mfma_f32_16x16x32_bf16 v[66:69], v[168:171], v[242:245], v[66:69]
	s_setprio 0
	s_barrier
	s_mov_b32 m0, s37
	s_add_u32 s76, s28, 0x80000
	s_addc_u32 s77, s29, 0
	ds_read_b128 v[172:175], v179 offset:16384
	ds_read_b128 v[202:205], v179 offset:17408
	ds_read_b128 v[206:209], v179 offset:18432
	ds_read_b128 v[210:213], v179 offset:19456
	ds_read_b128 v[214:217], v179 offset:20480
	ds_read_b128 v[218:221], v179 offset:21504
	ds_read_b128 v[222:225], v179 offset:22528
	ds_read_b128 v[242:245], v179 offset:23552
	global_load_lds_dwordx4 v64, s[28:29]
	s_mov_b32 m0, s38
	s_nop 0
	global_load_lds_dwordx4 v146, s[28:29]
	s_mov_b32 m0, s39
	s_nop 0
	global_load_lds_dwordx4 v64, s[76:77]
	s_mov_b32 m0, s40
	s_nop 0
	global_load_lds_dwordx4 v146, s[76:77]
	s_mov_b32 m0, s36
	s_nop 0
	global_load_lds_dwordx4 v150, s[30:31]
	s_mov_b32 m0, s41
	s_nop 0
	global_load_lds_dwordx4 v148, s[30:31]
	s_waitcnt vmcnt(8)
	s_waitcnt lgkmcnt(0)
	s_barrier
	s_setprio 1
	s_waitcnt lgkmcnt(0)
	v_mfma_f32_16x16x32_bf16 v[60:63], v[130:133], v[172:175], v[60:63]
	v_mfma_f32_16x16x32_bf16 v[56:59], v[138:141], v[172:175], v[56:59]
	v_mfma_f32_16x16x32_bf16 v[44:47], v[130:133], v[206:209], v[44:47]
	v_mfma_f32_16x16x32_bf16 v[40:43], v[138:141], v[206:209], v[40:43]
	v_mfma_f32_16x16x32_bf16 v[28:31], v[130:133], v[214:217], v[28:31]
	v_mfma_f32_16x16x32_bf16 v[24:27], v[138:141], v[214:217], v[24:27]
	v_mfma_f32_16x16x32_bf16 v[12:15], v[130:133], v[222:225], v[12:15]
	v_mfma_f32_16x16x32_bf16 v[8:11], v[138:141], v[222:225], v[8:11]
	v_mfma_f32_16x16x32_bf16 v[60:63], v[134:137], v[202:205], v[60:63]
	v_mfma_f32_16x16x32_bf16 v[56:59], v[142:145], v[202:205], v[56:59]
	v_mfma_f32_16x16x32_bf16 v[44:47], v[134:137], v[210:213], v[44:47]
	v_mfma_f32_16x16x32_bf16 v[40:43], v[142:145], v[210:213], v[40:43]
	v_mfma_f32_16x16x32_bf16 v[28:31], v[134:137], v[218:221], v[28:31]
	v_mfma_f32_16x16x32_bf16 v[24:27], v[142:145], v[218:221], v[24:27]
	v_mfma_f32_16x16x32_bf16 v[12:15], v[134:137], v[242:245], v[12:15]
	v_mfma_f32_16x16x32_bf16 v[8:11], v[142:145], v[242:245], v[8:11]
	s_setprio 0
	s_setprio 1
	v_mfma_f32_16x16x32_bf16 v[52:55], v[156:159], v[172:175], v[52:55]
	v_mfma_f32_16x16x32_bf16 v[48:51], v[164:167], v[172:175], v[48:51]
	v_mfma_f32_16x16x32_bf16 v[36:39], v[156:159], v[206:209], v[36:39]
	v_mfma_f32_16x16x32_bf16 v[32:35], v[164:167], v[206:209], v[32:35]
	v_mfma_f32_16x16x32_bf16 v[20:23], v[156:159], v[214:217], v[20:23]
	v_mfma_f32_16x16x32_bf16 v[16:19], v[164:167], v[214:217], v[16:19]
	v_mfma_f32_16x16x32_bf16 v[4:7], v[156:159], v[222:225], v[4:7]
	v_mfma_f32_16x16x32_bf16 v[0:3], v[164:167], v[222:225], v[0:3]
	v_mfma_f32_16x16x32_bf16 v[52:55], v[160:163], v[202:205], v[52:55]
	v_mfma_f32_16x16x32_bf16 v[48:51], v[168:171], v[202:205], v[48:51]
	v_mfma_f32_16x16x32_bf16 v[36:39], v[160:163], v[210:213], v[36:39]
	v_mfma_f32_16x16x32_bf16 v[32:35], v[168:171], v[210:213], v[32:35]
	v_mfma_f32_16x16x32_bf16 v[20:23], v[160:163], v[218:221], v[20:23]
	v_mfma_f32_16x16x32_bf16 v[16:19], v[168:171], v[218:221], v[16:19]
	v_mfma_f32_16x16x32_bf16 v[4:7], v[160:163], v[242:245], v[4:7]
	v_mfma_f32_16x16x32_bf16 v[0:3], v[168:171], v[242:245], v[0:3]
	s_setprio 0
	s_barrier
	ds_read_b128 v[130:133], v241 offset:32768
	ds_read_b128 v[134:137], v241 offset:33792
	ds_read_b128 v[138:141], v241 offset:34816
	ds_read_b128 v[142:145], v241 offset:35840
	ds_read_b128 v[156:159], v241 offset:49152
	ds_read_b128 v[160:163], v241 offset:50176
	ds_read_b128 v[164:167], v241 offset:51200
	ds_read_b128 v[168:171], v241 offset:52224
	s_add_u32 s56, s30, 0x80000
	s_addc_u32 s57, s31, 0
	s_mov_b32 m0, s42
	ds_read_b128 v[172:175], v179 offset:32768
	ds_read_b128 v[202:205], v179 offset:33792
	ds_read_b128 v[206:209], v179 offset:34816
	ds_read_b128 v[210:213], v179 offset:35840
	ds_read_b128 v[214:217], v179 offset:36864
	ds_read_b128 v[218:221], v179 offset:37888
	ds_read_b128 v[222:225], v179 offset:38912
	ds_read_b128 v[242:245], v179 offset:39936
	global_load_lds_dwordx4 v150, s[56:57]
	s_mov_b32 m0, s43
	s_nop 0
	global_load_lds_dwordx4 v148, s[56:57]
	s_waitcnt vmcnt(8)
	s_waitcnt lgkmcnt(0)
	s_barrier
	s_setprio 1
	s_waitcnt lgkmcnt(0)
	v_mfma_f32_16x16x32_bf16 v[126:129], v[130:133], v[172:175], v[126:129]
	v_mfma_f32_16x16x32_bf16 v[122:125], v[138:141], v[172:175], v[122:125]
	v_mfma_f32_16x16x32_bf16 v[110:113], v[130:133], v[206:209], v[110:113]
	v_mfma_f32_16x16x32_bf16 v[106:109], v[138:141], v[206:209], v[106:109]
	v_mfma_f32_16x16x32_bf16 v[94:97], v[130:133], v[214:217], v[94:97]
	v_mfma_f32_16x16x32_bf16 v[90:93], v[138:141], v[214:217], v[90:93]
	v_mfma_f32_16x16x32_bf16 v[78:81], v[130:133], v[222:225], v[78:81]
	v_mfma_f32_16x16x32_bf16 v[74:77], v[138:141], v[222:225], v[74:77]
	v_mfma_f32_16x16x32_bf16 v[126:129], v[134:137], v[202:205], v[126:129]
	v_mfma_f32_16x16x32_bf16 v[122:125], v[142:145], v[202:205], v[122:125]
	v_mfma_f32_16x16x32_bf16 v[110:113], v[134:137], v[210:213], v[110:113]
	v_mfma_f32_16x16x32_bf16 v[106:109], v[142:145], v[210:213], v[106:109]
	v_mfma_f32_16x16x32_bf16 v[94:97], v[134:137], v[218:221], v[94:97]
	v_mfma_f32_16x16x32_bf16 v[90:93], v[142:145], v[218:221], v[90:93]
	v_mfma_f32_16x16x32_bf16 v[78:81], v[134:137], v[242:245], v[78:81]
	v_mfma_f32_16x16x32_bf16 v[74:77], v[142:145], v[242:245], v[74:77]
	s_setprio 0
	s_setprio 1
	v_mfma_f32_16x16x32_bf16 v[118:121], v[156:159], v[172:175], v[118:121]
	v_mfma_f32_16x16x32_bf16 v[114:117], v[164:167], v[172:175], v[114:117]
	v_mfma_f32_16x16x32_bf16 v[102:105], v[156:159], v[206:209], v[102:105]
	v_mfma_f32_16x16x32_bf16 v[98:101], v[164:167], v[206:209], v[98:101]
	v_mfma_f32_16x16x32_bf16 v[86:89], v[156:159], v[214:217], v[86:89]
	v_mfma_f32_16x16x32_bf16 v[82:85], v[164:167], v[214:217], v[82:85]
	v_mfma_f32_16x16x32_bf16 v[70:73], v[156:159], v[222:225], v[70:73]
	v_mfma_f32_16x16x32_bf16 v[66:69], v[164:167], v[222:225], v[66:69]
	v_mfma_f32_16x16x32_bf16 v[118:121], v[160:163], v[202:205], v[118:121]
	v_mfma_f32_16x16x32_bf16 v[114:117], v[168:171], v[202:205], v[114:117]
	v_mfma_f32_16x16x32_bf16 v[102:105], v[160:163], v[210:213], v[102:105]
	v_mfma_f32_16x16x32_bf16 v[98:101], v[168:171], v[210:213], v[98:101]
	v_mfma_f32_16x16x32_bf16 v[86:89], v[160:163], v[218:221], v[86:89]
	v_mfma_f32_16x16x32_bf16 v[82:85], v[168:171], v[218:221], v[82:85]
	v_mfma_f32_16x16x32_bf16 v[70:73], v[160:163], v[242:245], v[70:73]
	v_mfma_f32_16x16x32_bf16 v[66:69], v[168:171], v[242:245], v[66:69]
	s_setprio 0
	s_barrier
	s_add_i32 m0, s46, 0xffffff80
	s_add_u32 s58, s28, 0x80080
	s_addc_u32 s59, s29, 0
	ds_read_b128 v[172:175], v179 offset:49152
	ds_read_b128 v[202:205], v179 offset:50176
	ds_read_b128 v[206:209], v179 offset:51200
	ds_read_b128 v[210:213], v179 offset:52224
	ds_read_b128 v[214:217], v179 offset:53248
	ds_read_b128 v[218:221], v179 offset:54272
	ds_read_b128 v[222:225], v179 offset:55296
	ds_read_b128 v[242:245], v179 offset:56320
	global_load_lds_dwordx4 v64, s[28:29] offset:128
	s_add_i32 m0, s47, 0xffffff80
	s_nop 0
	global_load_lds_dwordx4 v146, s[28:29] offset:128
	s_mov_b32 m0, s50
	s_nop 0
	global_load_lds_dwordx4 v64, s[58:59]
	s_mov_b32 m0, s51
	s_nop 0
	global_load_lds_dwordx4 v146, s[58:59]
	s_add_i32 m0, s48, 0xffffff80
	s_nop 0
	global_load_lds_dwordx4 v150, s[30:31] offset:128
	s_add_i32 m0, s49, 0xffffff80
	s_nop 0
	global_load_lds_dwordx4 v148, s[30:31] offset:128
	s_waitcnt vmcnt(8)
	s_waitcnt lgkmcnt(0)
	s_barrier
	s_setprio 1
	s_waitcnt lgkmcnt(0)
	v_mfma_f32_16x16x32_bf16 v[60:63], v[130:133], v[172:175], v[60:63]
	v_mfma_f32_16x16x32_bf16 v[56:59], v[138:141], v[172:175], v[56:59]
	v_mfma_f32_16x16x32_bf16 v[44:47], v[130:133], v[206:209], v[44:47]
	v_mfma_f32_16x16x32_bf16 v[40:43], v[138:141], v[206:209], v[40:43]
	v_mfma_f32_16x16x32_bf16 v[28:31], v[130:133], v[214:217], v[28:31]
	v_mfma_f32_16x16x32_bf16 v[24:27], v[138:141], v[214:217], v[24:27]
	v_mfma_f32_16x16x32_bf16 v[12:15], v[130:133], v[222:225], v[12:15]
	v_mfma_f32_16x16x32_bf16 v[8:11], v[138:141], v[222:225], v[8:11]
	v_mfma_f32_16x16x32_bf16 v[60:63], v[134:137], v[202:205], v[60:63]
	v_mfma_f32_16x16x32_bf16 v[56:59], v[142:145], v[202:205], v[56:59]
	v_mfma_f32_16x16x32_bf16 v[44:47], v[134:137], v[210:213], v[44:47]
	v_mfma_f32_16x16x32_bf16 v[40:43], v[142:145], v[210:213], v[40:43]
	v_mfma_f32_16x16x32_bf16 v[28:31], v[134:137], v[218:221], v[28:31]
	v_mfma_f32_16x16x32_bf16 v[24:27], v[142:145], v[218:221], v[24:27]
	v_mfma_f32_16x16x32_bf16 v[12:15], v[134:137], v[242:245], v[12:15]
	v_mfma_f32_16x16x32_bf16 v[8:11], v[142:145], v[242:245], v[8:11]
	s_setprio 0
	s_setprio 1
	v_mfma_f32_16x16x32_bf16 v[52:55], v[156:159], v[172:175], v[52:55]
	v_mfma_f32_16x16x32_bf16 v[48:51], v[164:167], v[172:175], v[48:51]
	v_mfma_f32_16x16x32_bf16 v[36:39], v[156:159], v[206:209], v[36:39]
	v_mfma_f32_16x16x32_bf16 v[32:35], v[164:167], v[206:209], v[32:35]
	v_mfma_f32_16x16x32_bf16 v[20:23], v[156:159], v[214:217], v[20:23]
	v_mfma_f32_16x16x32_bf16 v[16:19], v[164:167], v[214:217], v[16:19]
	v_mfma_f32_16x16x32_bf16 v[4:7], v[156:159], v[222:225], v[4:7]
	v_mfma_f32_16x16x32_bf16 v[0:3], v[164:167], v[222:225], v[0:3]
	v_mfma_f32_16x16x32_bf16 v[52:55], v[160:163], v[202:205], v[52:55]
	v_mfma_f32_16x16x32_bf16 v[48:51], v[168:171], v[202:205], v[48:51]
	v_mfma_f32_16x16x32_bf16 v[36:39], v[160:163], v[210:213], v[36:39]
	v_mfma_f32_16x16x32_bf16 v[32:35], v[168:171], v[210:213], v[32:35]
	v_mfma_f32_16x16x32_bf16 v[20:23], v[160:163], v[218:221], v[20:23]
	v_mfma_f32_16x16x32_bf16 v[16:19], v[168:171], v[218:221], v[16:19]
	v_mfma_f32_16x16x32_bf16 v[4:7], v[160:163], v[242:245], v[4:7]
	v_mfma_f32_16x16x32_bf16 v[0:3], v[168:171], v[242:245], v[0:3]
	s_setprio 0
	s_barrier
	s_add_i32 s74, s74, 2
	s_add_u32 s10, s10, 0x100
	s_addc_u32 s11, s11, 0
	s_add_u32 s72, s72, 0x100
	s_addc_u32 s73, s73, 0
	s_cmp_gt_u32 s74, 29
	s_cbranch_scc0 .LBB0_323
	s_and_b64 vcc, exec, s[16:17]
	s_cbranch_vccz .LBB0_326
	s_barrier
